# LDS bank conflicts: XOR swizzle (bits 3-4 of the key offset with (row>>3)&3) on the GLA output phase's transposed-V image, stores and operand reads; 4-way -> 2-way
# speedup vs baseline: 1.0001x; 1.0001x over previous
.LBB0_518:
	s_and_b64 vcc, exec, s[6:7]
	s_cbranch_vccnz .LBB0_554
	s_add_u32 s22, s8, 0x7e00000
	v_bfe_u32 v33, v0, 4, 2
	s_addc_u32 s23, s9, 0
	v_and_b32_e32 v23, 3, v0
	v_lshlrev_b32_e32 v26, 4, v33
	v_mov_b32_e32 v27, v2
	v_lshl_add_u32 v25, v157, 16, 0
	v_and_or_b32 v35, v24, 24, v23
	v_lshl_add_u64 v[28:29], s[8:9], 0, v[26:27]
	s_mov_b64 s[6:7], 0x1ae00000
	v_lshlrev_b32_e32 v23, 3, v0
	s_cmp_gt_i32 s16, -1
	v_lshl_add_u32 v234, v20, 2, v25
	v_and_b32_e32 v31, 15, v0
	v_lshl_add_u64 v[148:149], v[28:29], 0, s[6:7]
	v_lshrrev_b32_e32 v28, 1, v208
	v_and_b32_e32 v28, 0x78, v28
	v_mov_b32_e32 v23, v2
	v_and_b32_e32 v30, 64, v211
	s_cselect_b64 s[38:39], -1, 0
	s_cmp_eq_u32 s16, 0
	v_lshl_or_b32 v235, v3, 4, v31
	v_sub_u32_e32 v27, v234, v22
	v_lshl_add_u64 v[150:151], s[10:11], 0, v[22:23]
	s_movk_i32 s6, 0x90
	v_xor_b32_e32 v22, 16, v211
	v_add_u32_e32 v30, 64, v30
	s_cselect_b64 s[40:41], -1, 0
	s_cmp_gt_i32 s16, 0
	v_mad_u32_u24 v23, v235, s6, v25
	v_cmp_lt_i32_e32 vcc, v22, v30
	s_movk_i32 s6, 0x5f
	s_cselect_b64 s[42:43], -1, 0
	s_cmp_eq_u32 s16, 1
	v_cndmask_b32_e32 v22, v211, v22, vcc
	v_cmp_gt_u32_sdwa s[28:29], v0, s6 src0_sel:BYTE_0 src1_sel:DWORD
	s_movk_i32 s6, 0x7f
	s_cselect_b64 s[44:45], -1, 0
	s_cmp_gt_i32 s16, 1
	v_lshlrev_b32_e32 v237, 2, v22
	v_xor_b32_e32 v22, 32, v211
	v_cmp_gt_u32_sdwa s[30:31], v0, s6 src0_sel:BYTE_0 src1_sel:DWORD
	s_movk_i32 s6, 0x9f
	s_cselect_b64 s[46:47], -1, 0
	s_cmp_eq_u32 s16, 2
	v_lshlrev_b32_e32 v39, 2, v33
	v_cmp_lt_i32_e32 vcc, v22, v30
	v_cmp_gt_u32_sdwa s[34:35], v0, s6 src0_sel:BYTE_0 src1_sel:DWORD
	s_movk_i32 s6, 0xbf
	s_cselect_b64 s[48:49], -1, 0
	s_cmp_gt_i32 s16, 2
	v_lshlrev_b32_e32 v3, 8, v1
	v_lshlrev_b32_e32 v236, 3, v1
	v_cndmask_b32_e32 v22, v211, v22, vcc
	v_cmp_gt_u32_sdwa s[24:25], v0, v218 src0_sel:BYTE_0 src1_sel:DWORD
	v_cmp_gt_u32_sdwa s[26:27], v0, v214 src0_sel:BYTE_0 src1_sel:DWORD
	v_cmp_gt_u32_sdwa s[36:37], v0, s6 src0_sel:BYTE_0 src1_sel:DWORD
	v_cmp_eq_u32_e64 s[6:7], 7, v1
	v_mul_u32_u24_e32 v0, 0x240, v1
	v_lshlrev_b32_e32 v240, 1, v208
	v_and_b32_e32 v240, 30, v240
	v_or_b32_e32 v1, 2, v39
	s_cselect_b64 s[50:51], -1, 0
	s_cmp_eq_u32 s16, 3
	v_lshlrev_b32_e32 v24, 3, v33
	v_mul_u32_u24_e32 v29, 0x90, v28
	v_lshlrev_b32_e32 v238, 2, v22
	v_lshlrev_b32_e32 v22, 6, v35
	v_lshl_add_u32 v239, v0, 1, v27
	v_lshlrev_b32_e32 v0, 1, v240
	v_cmp_gt_u32_e64 s[12:13], v1, v31
	v_or_b32_e32 v1, 3, v39
	s_cselect_b64 s[52:53], -1, 0
	s_add_i32 s16, 0, 0x20000
	v_add_u32_e32 v37, v25, v26
	v_add_u32_e32 v41, v25, v24
	v_or_b32_e32 v30, 0x100, v22
	v_or_b32_e32 v32, 0x800, v22
	v_or_b32_e32 v34, 0x900, v22
	v_or_b32_e32 v36, 0x1000, v22
	v_or_b32_e32 v38, 0x1100, v22
	v_or_b32_e32 v40, 0x1800, v22
	v_or_b32_e32 v42, 0x1900, v22
	v_and_b32_e32 v241, 24, v28
	v_xor_b32_e32 v241, v241, v0
	v_add3_u32 v241, v25, v29, v241
	v_mul_u32_u24_e32 v0, 0x90, v31
	v_cmp_gt_u32_e64 s[14:15], v1, v31
	v_mul_u32_u24_e32 v1, 0x90, v35
	v_lshl_add_u32 v243, v33, 5, s16
	v_or_b32_e32 v242, 32, v240
	v_cmp_gt_u32_e64 s[8:9], v39, v31
	v_cmp_lt_u32_e64 s[10:11], v39, v31
	v_add_u32_e32 v244, 0x80, v243
	v_add_u32_e32 v245, 0x100, v243
	v_add_u32_e32 v246, 0x180, v243
	v_lshlrev_b32_e32 v247, 6, v157
	v_lshlrev_b32_e32 v248, 4, v157
	v_lshlrev_b32_e32 v182, 1, v24
	v_lshlrev_b32_e32 v184, 1, v22
	v_lshlrev_b32_e32 v186, 1, v30
	v_lshlrev_b32_e32 v188, 1, v32
	v_lshlrev_b32_e32 v190, 1, v34
	v_lshlrev_b32_e32 v192, 1, v36
	v_lshlrev_b32_e32 v194, 1, v38
	v_lshlrev_b32_e32 v196, 1, v40
	v_lshlrev_b32_e32 v198, 1, v42
	v_add_u32_e32 v249, v234, v3
	v_lshlrev_b32_e32 v200, 1, v20
	v_lshlrev_b32_e32 v202, 1, v28
	v_add_u32_e32 v250, v23, v26
	v_add_u32_e32 v251, v37, v0
	v_and_b32_e32 v252, 24, v35
	v_xor_b32_e32 v252, v252, v24
	v_add3_u32 v252, v25, v252, v1
	s_mov_b32 s56, s78
	s_branch .LBB0_522
